# K-loop load segments: one LDS base reg + immediate offsets (no per-iteration v_add), M0 = s15 + literal in one SALU op, tail pointer increments fill M0 wait slots; st5 K-loop DMA in scalar-base form
# speedup vs baseline: 1.0075x; 1.0008x over previous
.LBB0_119:
	s_add_u32 s17, s10, s24
	s_addc_u32 s31, s11, s25
	s_add_u32 s30, s17, 0x100
	s_addc_u32 s49, s31, 0
	s_and_b64 s[28:29], s[22:23], exec
	s_cselect_b32 s29, s19, s49
	s_cselect_b32 s28, s18, s30
	s_add_u32 s24, s8, s24
	s_addc_u32 s25, s9, s25
	s_add_u32 s24, s24, 0x100
	s_addc_u32 s25, s25, 0
	s_add_i32 s49, 0, 0x10000
	v_add_u32_e32 v74, s49, v77
	ds_read_b128 v[70:73], v74
	ds_read_b128 v[154:157], v74 offset:1024
	ds_read_b128 v[186:189], v74 offset:2048
	ds_read_b128 v[190:193], v74 offset:3072
	s_and_b64 s[22:23], s[22:23], exec
	s_cselect_b32 s24, s20, s24
	s_cselect_b32 s25, s21, s25
	s_add_u32 s30, s17, 0x40080
	s_addc_u32 s31, s31, 0
	s_add_i32 s52, s49, s36
	s_add_i32 m0, s37, 0xc000
	s_add_i32 s17, s37, 0xe000
	s_add_i32 s55, s52, 0x2000
	s_add_i32 s56, 0, 0x18000
	s_add_u32 s22, s28, 0x40000
	s_addc_u32 s23, s29, 0
	s_add_i32 s49, s56, s36
	s_add_i32 s57, s49, 0x2000
	ds_read_b128 v[194:197], v109
	ds_read_b128 v[198:201], v109 offset:1024
	ds_read_b128 v[202:205], v109 offset:2048
	ds_read_b128 v[206:209], v109 offset:3072
	ds_read_b128 v[210:213], v109 offset:4096
	ds_read_b128 v[214:217], v109 offset:5120
	ds_read_b128 v[218:221], v109 offset:6144
	ds_read_b128 v[222:225], v109 offset:7168
	global_load_lds_dwordx4 v64, s[30:31]
	s_mov_b32 m0, s17
	s_nop 0
	global_load_lds_dwordx4 v66, s[30:31]
	s_waitcnt vmcnt(6)
	s_waitcnt lgkmcnt(0)
	s_barrier
	s_setprio 1
	s_waitcnt lgkmcnt(0)
	v_mfma_f32_16x16x32_bf16 v[60:63], v[70:73], v[194:197], v[60:63]
	v_mfma_f32_16x16x32_bf16 v[56:59], v[186:189], v[194:197], v[56:59]
	v_mfma_f32_16x16x32_bf16 v[52:55], v[70:73], v[202:205], v[52:55]
	v_mfma_f32_16x16x32_bf16 v[48:51], v[186:189], v[202:205], v[48:51]
	v_mfma_f32_16x16x32_bf16 v[44:47], v[70:73], v[210:213], v[44:47]
	v_mfma_f32_16x16x32_bf16 v[40:43], v[186:189], v[210:213], v[40:43]
	v_mfma_f32_16x16x32_bf16 v[36:39], v[70:73], v[218:221], v[36:39]
	v_mfma_f32_16x16x32_bf16 v[32:35], v[186:189], v[218:221], v[32:35]
	v_mfma_f32_16x16x32_bf16 v[60:63], v[154:157], v[198:201], v[60:63]
	v_mfma_f32_16x16x32_bf16 v[56:59], v[190:193], v[198:201], v[56:59]
	v_mfma_f32_16x16x32_bf16 v[52:55], v[154:157], v[206:209], v[52:55]
	v_mfma_f32_16x16x32_bf16 v[48:51], v[190:193], v[206:209], v[48:51]
	v_mfma_f32_16x16x32_bf16 v[44:47], v[154:157], v[214:217], v[44:47]
	v_mfma_f32_16x16x32_bf16 v[40:43], v[190:193], v[214:217], v[40:43]
	v_mfma_f32_16x16x32_bf16 v[36:39], v[154:157], v[222:225], v[36:39]
	v_mfma_f32_16x16x32_bf16 v[32:35], v[190:193], v[222:225], v[32:35]
	s_setprio 0
	s_barrier
	s_mov_b32 m0, s52
	ds_read_b128 v[194:197], v109 offset:16384
	ds_read_b128 v[198:201], v109 offset:17408
	ds_read_b128 v[202:205], v109 offset:18432
	ds_read_b128 v[206:209], v109 offset:19456
	ds_read_b128 v[210:213], v109 offset:20480
	ds_read_b128 v[214:217], v109 offset:21504
	ds_read_b128 v[218:221], v109 offset:22528
	ds_read_b128 v[222:225], v109 offset:23552
	global_load_lds_dwordx4 v144, s[24:25]
	s_mov_b32 m0, s55
	s_nop 0
	global_load_lds_dwordx4 v68, s[24:25]
	s_mov_b32 m0, s37
	s_nop 0
	global_load_lds_dwordx4 v64, s[28:29]
	s_mov_b32 m0, s38
	s_nop 0
	global_load_lds_dwordx4 v66, s[28:29]
	s_waitcnt vmcnt(6)
	s_waitcnt lgkmcnt(0)
	s_barrier
	s_setprio 1
	s_waitcnt lgkmcnt(0)
	v_mfma_f32_16x16x32_bf16 v[28:31], v[70:73], v[194:197], v[28:31]
	v_mfma_f32_16x16x32_bf16 v[24:27], v[186:189], v[194:197], v[24:27]
	v_mfma_f32_16x16x32_bf16 v[20:23], v[70:73], v[202:205], v[20:23]
	v_mfma_f32_16x16x32_bf16 v[16:19], v[186:189], v[202:205], v[16:19]
	v_mfma_f32_16x16x32_bf16 v[12:15], v[70:73], v[210:213], v[12:15]
	v_mfma_f32_16x16x32_bf16 v[8:11], v[186:189], v[210:213], v[8:11]
	v_mfma_f32_16x16x32_bf16 v[4:7], v[70:73], v[218:221], v[4:7]
	v_mfma_f32_16x16x32_bf16 v[0:3], v[186:189], v[218:221], v[0:3]
	v_mfma_f32_16x16x32_bf16 v[28:31], v[154:157], v[198:201], v[28:31]
	v_mfma_f32_16x16x32_bf16 v[24:27], v[190:193], v[198:201], v[24:27]
	v_mfma_f32_16x16x32_bf16 v[20:23], v[154:157], v[206:209], v[20:23]
	v_mfma_f32_16x16x32_bf16 v[16:19], v[190:193], v[206:209], v[16:19]
	v_mfma_f32_16x16x32_bf16 v[12:15], v[154:157], v[214:217], v[12:15]
	v_mfma_f32_16x16x32_bf16 v[8:11], v[190:193], v[214:217], v[8:11]
	v_mfma_f32_16x16x32_bf16 v[4:7], v[154:157], v[222:225], v[4:7]
	v_mfma_f32_16x16x32_bf16 v[0:3], v[190:193], v[222:225], v[0:3]
	s_setprio 0
	s_barrier
	v_add_u32_e32 v160, s56, v77
	ds_read_b128 v[70:73], v160
	ds_read_b128 v[154:157], v160 offset:1024
	ds_read_b128 v[186:189], v160 offset:2048
	ds_read_b128 v[190:193], v160 offset:3072
	s_mov_b32 m0, s39
	ds_read_b128 v[194:197], v109 offset:32768
	ds_read_b128 v[198:201], v109 offset:33792
	ds_read_b128 v[202:205], v109 offset:34816
	ds_read_b128 v[206:209], v109 offset:35840
	ds_read_b128 v[210:213], v109 offset:36864
	ds_read_b128 v[214:217], v109 offset:37888
	ds_read_b128 v[218:221], v109 offset:38912
	ds_read_b128 v[222:225], v109 offset:39936
	global_load_lds_dwordx4 v64, s[22:23]
	s_mov_b32 m0, s40
	s_nop 0
	global_load_lds_dwordx4 v66, s[22:23]
	s_waitcnt vmcnt(6)
	s_waitcnt lgkmcnt(0)
	s_barrier
	s_setprio 1
	s_waitcnt lgkmcnt(0)
	v_mfma_f32_16x16x32_bf16 v[60:63], v[70:73], v[194:197], v[60:63]
	v_mfma_f32_16x16x32_bf16 v[56:59], v[186:189], v[194:197], v[56:59]
	v_mfma_f32_16x16x32_bf16 v[52:55], v[70:73], v[202:205], v[52:55]
	v_mfma_f32_16x16x32_bf16 v[48:51], v[186:189], v[202:205], v[48:51]
	v_mfma_f32_16x16x32_bf16 v[44:47], v[70:73], v[210:213], v[44:47]
	v_mfma_f32_16x16x32_bf16 v[40:43], v[186:189], v[210:213], v[40:43]
	v_mfma_f32_16x16x32_bf16 v[36:39], v[70:73], v[218:221], v[36:39]
	v_mfma_f32_16x16x32_bf16 v[32:35], v[186:189], v[218:221], v[32:35]
	v_mfma_f32_16x16x32_bf16 v[60:63], v[154:157], v[198:201], v[60:63]
	v_mfma_f32_16x16x32_bf16 v[56:59], v[190:193], v[198:201], v[56:59]
	v_mfma_f32_16x16x32_bf16 v[52:55], v[154:157], v[206:209], v[52:55]
	v_mfma_f32_16x16x32_bf16 v[48:51], v[190:193], v[206:209], v[48:51]
	v_mfma_f32_16x16x32_bf16 v[44:47], v[154:157], v[214:217], v[44:47]
	v_mfma_f32_16x16x32_bf16 v[40:43], v[190:193], v[214:217], v[40:43]
	v_mfma_f32_16x16x32_bf16 v[36:39], v[154:157], v[222:225], v[36:39]
	v_mfma_f32_16x16x32_bf16 v[32:35], v[190:193], v[222:225], v[32:35]
	s_setprio 0
	s_barrier
	s_add_i32 m0, s49, 0xffffff80
	ds_read_b128 v[194:197], v109 offset:49152
	ds_read_b128 v[198:201], v109 offset:50176
	ds_read_b128 v[202:205], v109 offset:51200
	ds_read_b128 v[206:209], v109 offset:52224
	ds_read_b128 v[210:213], v109 offset:53248
	ds_read_b128 v[214:217], v109 offset:54272
	ds_read_b128 v[218:221], v109 offset:55296
	ds_read_b128 v[222:225], v109 offset:56320
	global_load_lds_dwordx4 v144, s[24:25] offset:128
	s_add_i32 m0, s57, 0xffffff80
	s_nop 0
	global_load_lds_dwordx4 v68, s[24:25] offset:128
	s_add_i32 m0, s42, 0xffffff80
	s_nop 0
	global_load_lds_dwordx4 v64, s[28:29] offset:128
	s_add_i32 m0, s43, 0xffffff80
	s_nop 0
	global_load_lds_dwordx4 v66, s[28:29] offset:128
	s_waitcnt vmcnt(6)
	s_waitcnt lgkmcnt(0)
	s_barrier
	s_setprio 1
	s_waitcnt lgkmcnt(0)
	v_mfma_f32_16x16x32_bf16 v[28:31], v[70:73], v[194:197], v[28:31]
	v_mfma_f32_16x16x32_bf16 v[24:27], v[186:189], v[194:197], v[24:27]
	v_mfma_f32_16x16x32_bf16 v[20:23], v[70:73], v[202:205], v[20:23]
	v_mfma_f32_16x16x32_bf16 v[16:19], v[186:189], v[202:205], v[16:19]
	v_mfma_f32_16x16x32_bf16 v[12:15], v[70:73], v[210:213], v[12:15]
	v_mfma_f32_16x16x32_bf16 v[8:11], v[186:189], v[210:213], v[8:11]
	v_mfma_f32_16x16x32_bf16 v[4:7], v[70:73], v[218:221], v[4:7]
	v_mfma_f32_16x16x32_bf16 v[0:3], v[186:189], v[218:221], v[0:3]
	v_mfma_f32_16x16x32_bf16 v[28:31], v[154:157], v[198:201], v[28:31]
	v_mfma_f32_16x16x32_bf16 v[24:27], v[190:193], v[198:201], v[24:27]
	v_mfma_f32_16x16x32_bf16 v[20:23], v[154:157], v[206:209], v[20:23]
	v_mfma_f32_16x16x32_bf16 v[16:19], v[190:193], v[206:209], v[16:19]
	v_mfma_f32_16x16x32_bf16 v[12:15], v[154:157], v[214:217], v[12:15]
	v_mfma_f32_16x16x32_bf16 v[8:11], v[190:193], v[214:217], v[8:11]
	v_mfma_f32_16x16x32_bf16 v[4:7], v[154:157], v[222:225], v[4:7]
	v_mfma_f32_16x16x32_bf16 v[0:3], v[190:193], v[222:225], v[0:3]
	s_setprio 0
	s_barrier
	s_andn2_b64 vcc, exec, s[12:13]
	s_mov_b64 s[22:23], -1
	s_mov_b64 s[12:13], 0
	s_mov_b64 s[24:25], 0x100
	s_cbranch_vccz .LBB0_119
	s_and_b64 vcc, exec, s[14:15]
	s_cbranch_vccz .LBB0_122
	s_barrier

.LBB0_245:
	s_add_u32 s6, s90, 0x80
	s_addc_u32 s7, s91, 0
	s_add_u32 s8, s42, 0x100
	v_mov_b32_e32 v0, 0
	s_addc_u32 s66, s43, 0
	s_mov_b32 s42, 0
	v_mov_b32_e32 v1, v0
	v_mov_b32_e32 v2, v0
	v_mov_b32_e32 v3, v0
	v_mov_b32_e32 v4, v0
	v_mov_b32_e32 v5, v0
	v_mov_b32_e32 v6, v0
	v_mov_b32_e32 v7, v0
	v_mov_b32_e32 v8, v0
	v_mov_b32_e32 v9, v0
	v_mov_b32_e32 v10, v0
	v_mov_b32_e32 v11, v0
	v_mov_b32_e32 v12, v0
	v_mov_b32_e32 v13, v0
	v_mov_b32_e32 v14, v0
	v_mov_b32_e32 v15, v0
	v_mov_b32_e32 v24, v0
	v_mov_b32_e32 v25, v0
	v_mov_b32_e32 v26, v0
	v_mov_b32_e32 v27, v0
	v_mov_b32_e32 v28, v0
	v_mov_b32_e32 v29, v0
	v_mov_b32_e32 v30, v0
	v_mov_b32_e32 v31, v0
	v_mov_b32_e32 v40, v0
	v_mov_b32_e32 v41, v0
	v_mov_b32_e32 v42, v0
	v_mov_b32_e32 v43, v0
	v_mov_b32_e32 v44, v0
	v_mov_b32_e32 v45, v0
	v_mov_b32_e32 v46, v0
	v_mov_b32_e32 v47, v0
	v_mov_b32_e32 v16, v0
	v_mov_b32_e32 v17, v0
	v_mov_b32_e32 v18, v0
	v_mov_b32_e32 v19, v0
	v_mov_b32_e32 v20, v0
	v_mov_b32_e32 v21, v0
	v_mov_b32_e32 v22, v0
	v_mov_b32_e32 v23, v0
	v_mov_b32_e32 v32, v0
	v_mov_b32_e32 v33, v0
	v_mov_b32_e32 v34, v0
	v_mov_b32_e32 v35, v0
	v_mov_b32_e32 v36, v0
	v_mov_b32_e32 v37, v0
	v_mov_b32_e32 v38, v0
	v_mov_b32_e32 v39, v0
	v_mov_b32_e32 v48, v0
	v_mov_b32_e32 v49, v0
	v_mov_b32_e32 v50, v0
	v_mov_b32_e32 v51, v0
	v_mov_b32_e32 v52, v0
	v_mov_b32_e32 v53, v0
	v_mov_b32_e32 v54, v0
	v_mov_b32_e32 v55, v0
	v_mov_b32_e32 v56, v0
	v_mov_b32_e32 v57, v0
	v_mov_b32_e32 v58, v0
	v_mov_b32_e32 v59, v0
	v_mov_b32_e32 v60, v0
	v_mov_b32_e32 v61, v0
	v_mov_b32_e32 v62, v0
	v_mov_b32_e32 v63, v0
	s_waitcnt lgkmcnt(0)
	v_mov_b32_e32 v64, v0
	v_mov_b32_e32 v65, v0
	v_mov_b32_e32 v66, v0
	v_mov_b32_e32 v67, v0
	v_mov_b32_e32 v68, v0
	v_mov_b32_e32 v69, v0
	v_mov_b32_e32 v70, v0
	v_mov_b32_e32 v71, v0
	v_mov_b32_e32 v72, v0
	v_mov_b32_e32 v73, v0
	v_mov_b32_e32 v74, v0
	v_mov_b32_e32 v75, v0
	v_mov_b32_e32 v76, v0
	v_mov_b32_e32 v77, v0
	v_mov_b32_e32 v78, v0
	v_mov_b32_e32 v79, v0
	v_mov_b32_e32 v88, v0
	v_mov_b32_e32 v89, v0
	v_mov_b32_e32 v90, v0
	v_mov_b32_e32 v91, v0
	v_mov_b32_e32 v92, v0
	v_mov_b32_e32 v93, v0
	v_mov_b32_e32 v94, v0
	v_mov_b32_e32 v95, v0
	v_mov_b32_e32 v104, v0
	v_mov_b32_e32 v105, v0
	v_mov_b32_e32 v106, v0
	v_mov_b32_e32 v107, v0
	v_mov_b32_e32 v108, v0
	v_mov_b32_e32 v109, v0
	v_mov_b32_e32 v110, v0
	v_mov_b32_e32 v111, v0
	v_mov_b32_e32 v80, v0
	v_mov_b32_e32 v81, v0
	v_mov_b32_e32 v82, v0
	v_mov_b32_e32 v83, v0
	v_mov_b32_e32 v84, v0
	v_mov_b32_e32 v85, v0
	v_mov_b32_e32 v86, v0
	v_mov_b32_e32 v87, v0
	v_mov_b32_e32 v96, v0
	v_mov_b32_e32 v97, v0
	v_mov_b32_e32 v98, v0
	v_mov_b32_e32 v99, v0
	v_mov_b32_e32 v100, v0
	v_mov_b32_e32 v101, v0
	v_mov_b32_e32 v102, v0
	v_mov_b32_e32 v103, v0
	v_mov_b32_e32 v112, v0
	v_mov_b32_e32 v113, v0
	v_mov_b32_e32 v114, v0
	v_mov_b32_e32 v115, v0
	v_mov_b32_e32 v116, v0
	v_mov_b32_e32 v117, v0
	v_mov_b32_e32 v118, v0
	v_mov_b32_e32 v119, v0
	v_mov_b32_e32 v120, v0
	v_mov_b32_e32 v121, v0
	v_mov_b32_e32 v122, v0
	v_mov_b32_e32 v123, v0
	v_mov_b32_e32 v124, v0
	v_mov_b32_e32 v125, v0
	v_mov_b32_e32 v126, v0
	v_mov_b32_e32 v127, v0
	v_add_u32_e32 v222, 0x10000, v157
.LBB0_246:
	s_add_i32 s90, s42, 2
	s_add_u32 s91, s6, 0x80
	s_addc_u32 s43, s7, 0
	s_cmp_eq_u32 s72, s42
	s_cselect_b32 s43, s89, s43
	s_cselect_b32 s42, s88, s91
	s_cselect_b32 s93, s1, s66
	s_cselect_b32 s92, s0, s8
	ds_read_b128 v[128:131], v222
	ds_read_b128 v[132:135], v222 offset:1024
	ds_read_b128 v[136:139], v222 offset:2048
	ds_read_b128 v[140:143], v222 offset:3072
	ds_read_b128 v[168:171], v222 offset:16384
	ds_read_b128 v[172:175], v222 offset:17408
	ds_read_b128 v[176:179], v222 offset:18432
	ds_read_b128 v[180:183], v222 offset:19456
	s_add_i32 m0, s68, 0xc000
	ds_read_b128 v[190:193], v188
	ds_read_b128 v[194:197], v188 offset:1024
	ds_read_b128 v[198:201], v188 offset:2048
	ds_read_b128 v[202:205], v188 offset:3072
	ds_read_b128 v[206:209], v188 offset:4096
	ds_read_b128 v[210:213], v188 offset:5120
	ds_read_b128 v[214:217], v188 offset:6144
	ds_read_b128 v[218:221], v188 offset:7168
	global_load_lds_dwordx4 v162, s[6:7]
	s_add_i32 m0, s68, 0xe000
	s_nop 0
	global_load_lds_dwordx4 v164, s[6:7]
	s_waitcnt vmcnt(8)
	s_waitcnt lgkmcnt(0)
	s_barrier
	s_setprio 1
	s_waitcnt lgkmcnt(0)
	v_mfma_f32_16x16x32_bf16 v[124:127], v[128:131], v[190:193], v[124:127]
	v_mfma_f32_16x16x32_bf16 v[120:123], v[136:139], v[190:193], v[120:123]
	v_mfma_f32_16x16x32_bf16 v[116:119], v[128:131], v[198:201], v[116:119]
	v_mfma_f32_16x16x32_bf16 v[112:115], v[136:139], v[198:201], v[112:115]
	v_mfma_f32_16x16x32_bf16 v[100:103], v[128:131], v[206:209], v[100:103]
	v_mfma_f32_16x16x32_bf16 v[96:99], v[136:139], v[206:209], v[96:99]
	v_mfma_f32_16x16x32_bf16 v[84:87], v[128:131], v[214:217], v[84:87]
	v_mfma_f32_16x16x32_bf16 v[80:83], v[136:139], v[214:217], v[80:83]
	v_mfma_f32_16x16x32_bf16 v[124:127], v[132:135], v[194:197], v[124:127]
	v_mfma_f32_16x16x32_bf16 v[120:123], v[140:143], v[194:197], v[120:123]
	v_mfma_f32_16x16x32_bf16 v[116:119], v[132:135], v[202:205], v[116:119]
	v_mfma_f32_16x16x32_bf16 v[112:115], v[140:143], v[202:205], v[112:115]
	v_mfma_f32_16x16x32_bf16 v[100:103], v[132:135], v[210:213], v[100:103]
	v_mfma_f32_16x16x32_bf16 v[96:99], v[140:143], v[210:213], v[96:99]
	v_mfma_f32_16x16x32_bf16 v[84:87], v[132:135], v[218:221], v[84:87]
	v_mfma_f32_16x16x32_bf16 v[80:83], v[140:143], v[218:221], v[80:83]
	s_setprio 0
	s_setprio 1
	v_mfma_f32_16x16x32_bf16 v[108:111], v[168:171], v[190:193], v[108:111]
	v_mfma_f32_16x16x32_bf16 v[104:107], v[176:179], v[190:193], v[104:107]
	v_mfma_f32_16x16x32_bf16 v[92:95], v[168:171], v[198:201], v[92:95]
	v_mfma_f32_16x16x32_bf16 v[88:91], v[176:179], v[198:201], v[88:91]
	v_mfma_f32_16x16x32_bf16 v[76:79], v[168:171], v[206:209], v[76:79]
	v_mfma_f32_16x16x32_bf16 v[72:75], v[176:179], v[206:209], v[72:75]
	v_mfma_f32_16x16x32_bf16 v[68:71], v[168:171], v[214:217], v[68:71]
	v_mfma_f32_16x16x32_bf16 v[64:67], v[176:179], v[214:217], v[64:67]
	v_mfma_f32_16x16x32_bf16 v[108:111], v[172:175], v[194:197], v[108:111]
	v_mfma_f32_16x16x32_bf16 v[104:107], v[180:183], v[194:197], v[104:107]
	v_mfma_f32_16x16x32_bf16 v[92:95], v[172:175], v[202:205], v[92:95]
	v_mfma_f32_16x16x32_bf16 v[88:91], v[180:183], v[202:205], v[88:91]
	v_mfma_f32_16x16x32_bf16 v[76:79], v[172:175], v[210:213], v[76:79]
	v_mfma_f32_16x16x32_bf16 v[72:75], v[180:183], v[210:213], v[72:75]
	v_mfma_f32_16x16x32_bf16 v[68:71], v[172:175], v[218:221], v[68:71]
	v_mfma_f32_16x16x32_bf16 v[64:67], v[180:183], v[218:221], v[64:67]
	s_setprio 0
	s_barrier
	s_add_i32 m0, s15, 0x10000
	ds_read_b128 v[190:193], v188 offset:16384
	ds_read_b128 v[194:197], v188 offset:17408
	ds_read_b128 v[198:201], v188 offset:18432
	ds_read_b128 v[202:205], v188 offset:19456
	ds_read_b128 v[206:209], v188 offset:20480
	ds_read_b128 v[210:213], v188 offset:21504
	ds_read_b128 v[214:217], v188 offset:22528
	ds_read_b128 v[218:221], v188 offset:23552
	global_load_lds_dwordx4 v148, s[92:93]
	s_add_i32 m0, s15, 0x12000
	s_nop 0
	global_load_lds_dwordx4 v152, s[92:93]
	s_add_i32 m0, s15, 0x14000
	s_add_u32 s92, s92, s21
	s_addc_u32 s93, s93, 0
	global_load_lds_dwordx4 v148, s[92:93]
	s_add_i32 m0, s15, 0x16000
	s_nop 0
	global_load_lds_dwordx4 v152, s[92:93]
	s_mov_b32 m0, s68
	s_nop 0
	global_load_lds_dwordx4 v146, s[42:43]
	s_mov_b32 m0, s23
	s_nop 0
	global_load_lds_dwordx4 v150, s[42:43]
	s_waitcnt vmcnt(8)
	s_waitcnt lgkmcnt(0)
	s_barrier
	s_setprio 1
	s_waitcnt lgkmcnt(0)
	v_mfma_f32_16x16x32_bf16 v[60:63], v[128:131], v[190:193], v[60:63]
	v_mfma_f32_16x16x32_bf16 v[56:59], v[136:139], v[190:193], v[56:59]
	v_mfma_f32_16x16x32_bf16 v[52:55], v[128:131], v[198:201], v[52:55]
	v_mfma_f32_16x16x32_bf16 v[48:51], v[136:139], v[198:201], v[48:51]
	v_mfma_f32_16x16x32_bf16 v[36:39], v[128:131], v[206:209], v[36:39]
	v_mfma_f32_16x16x32_bf16 v[32:35], v[136:139], v[206:209], v[32:35]
	v_mfma_f32_16x16x32_bf16 v[20:23], v[128:131], v[214:217], v[20:23]
	v_mfma_f32_16x16x32_bf16 v[16:19], v[136:139], v[214:217], v[16:19]
	v_mfma_f32_16x16x32_bf16 v[60:63], v[132:135], v[194:197], v[60:63]
	v_mfma_f32_16x16x32_bf16 v[56:59], v[140:143], v[194:197], v[56:59]
	v_mfma_f32_16x16x32_bf16 v[52:55], v[132:135], v[202:205], v[52:55]
	v_mfma_f32_16x16x32_bf16 v[48:51], v[140:143], v[202:205], v[48:51]
	v_mfma_f32_16x16x32_bf16 v[36:39], v[132:135], v[210:213], v[36:39]
	v_mfma_f32_16x16x32_bf16 v[32:35], v[140:143], v[210:213], v[32:35]
	v_mfma_f32_16x16x32_bf16 v[20:23], v[132:135], v[218:221], v[20:23]
	v_mfma_f32_16x16x32_bf16 v[16:19], v[140:143], v[218:221], v[16:19]
	s_setprio 0
	s_setprio 1
	v_mfma_f32_16x16x32_bf16 v[44:47], v[168:171], v[190:193], v[44:47]
	v_mfma_f32_16x16x32_bf16 v[40:43], v[176:179], v[190:193], v[40:43]
	v_mfma_f32_16x16x32_bf16 v[28:31], v[168:171], v[198:201], v[28:31]
	v_mfma_f32_16x16x32_bf16 v[24:27], v[176:179], v[198:201], v[24:27]
	v_mfma_f32_16x16x32_bf16 v[12:15], v[168:171], v[206:209], v[12:15]
	v_mfma_f32_16x16x32_bf16 v[8:11], v[176:179], v[206:209], v[8:11]
	v_mfma_f32_16x16x32_bf16 v[4:7], v[168:171], v[214:217], v[4:7]
	v_mfma_f32_16x16x32_bf16 v[0:3], v[176:179], v[214:217], v[0:3]
	v_mfma_f32_16x16x32_bf16 v[44:47], v[172:175], v[194:197], v[44:47]
	v_mfma_f32_16x16x32_bf16 v[40:43], v[180:183], v[194:197], v[40:43]
	v_mfma_f32_16x16x32_bf16 v[28:31], v[172:175], v[202:205], v[28:31]
	v_mfma_f32_16x16x32_bf16 v[24:27], v[180:183], v[202:205], v[24:27]
	v_mfma_f32_16x16x32_bf16 v[12:15], v[172:175], v[210:213], v[12:15]
	v_mfma_f32_16x16x32_bf16 v[8:11], v[180:183], v[210:213], v[8:11]
	v_mfma_f32_16x16x32_bf16 v[4:7], v[172:175], v[218:221], v[4:7]
	v_mfma_f32_16x16x32_bf16 v[0:3], v[180:183], v[218:221], v[0:3]
	s_setprio 0
	s_barrier
	ds_read_b128 v[128:131], v222 offset:32768
	ds_read_b128 v[132:135], v222 offset:33792
	ds_read_b128 v[136:139], v222 offset:34816
	ds_read_b128 v[140:143], v222 offset:35840
	ds_read_b128 v[168:171], v222 offset:49152
	ds_read_b128 v[172:175], v222 offset:50176
	ds_read_b128 v[176:179], v222 offset:51200
	ds_read_b128 v[180:183], v222 offset:52224
	s_add_u32 s42, s42, s48
	s_addc_u32 s43, s43, 0
	s_mov_b32 m0, s40
	ds_read_b128 v[190:193], v188 offset:32768
	ds_read_b128 v[194:197], v188 offset:33792
	ds_read_b128 v[198:201], v188 offset:34816
	ds_read_b128 v[202:205], v188 offset:35840
	ds_read_b128 v[206:209], v188 offset:36864
	ds_read_b128 v[210:213], v188 offset:37888
	ds_read_b128 v[214:217], v188 offset:38912
	ds_read_b128 v[218:221], v188 offset:39936
	global_load_lds_dwordx4 v146, s[42:43]
	s_mov_b32 m0, s41
	s_nop 0
	global_load_lds_dwordx4 v150, s[42:43]
	s_waitcnt vmcnt(8)
	s_waitcnt lgkmcnt(0)
	s_barrier
	s_setprio 1
	s_waitcnt lgkmcnt(0)
	v_mfma_f32_16x16x32_bf16 v[124:127], v[128:131], v[190:193], v[124:127]
	v_mfma_f32_16x16x32_bf16 v[120:123], v[136:139], v[190:193], v[120:123]
	v_mfma_f32_16x16x32_bf16 v[116:119], v[128:131], v[198:201], v[116:119]
	v_mfma_f32_16x16x32_bf16 v[112:115], v[136:139], v[198:201], v[112:115]
	v_mfma_f32_16x16x32_bf16 v[100:103], v[128:131], v[206:209], v[100:103]
	v_mfma_f32_16x16x32_bf16 v[96:99], v[136:139], v[206:209], v[96:99]
	v_mfma_f32_16x16x32_bf16 v[84:87], v[128:131], v[214:217], v[84:87]
	v_mfma_f32_16x16x32_bf16 v[80:83], v[136:139], v[214:217], v[80:83]
	v_mfma_f32_16x16x32_bf16 v[124:127], v[132:135], v[194:197], v[124:127]
	v_mfma_f32_16x16x32_bf16 v[120:123], v[140:143], v[194:197], v[120:123]
	v_mfma_f32_16x16x32_bf16 v[116:119], v[132:135], v[202:205], v[116:119]
	v_mfma_f32_16x16x32_bf16 v[112:115], v[140:143], v[202:205], v[112:115]
	v_mfma_f32_16x16x32_bf16 v[100:103], v[132:135], v[210:213], v[100:103]
	v_mfma_f32_16x16x32_bf16 v[96:99], v[140:143], v[210:213], v[96:99]
	v_mfma_f32_16x16x32_bf16 v[84:87], v[132:135], v[218:221], v[84:87]
	v_mfma_f32_16x16x32_bf16 v[80:83], v[140:143], v[218:221], v[80:83]
	s_setprio 0
	s_setprio 1
	v_mfma_f32_16x16x32_bf16 v[108:111], v[168:171], v[190:193], v[108:111]
	v_mfma_f32_16x16x32_bf16 v[104:107], v[176:179], v[190:193], v[104:107]
	v_mfma_f32_16x16x32_bf16 v[92:95], v[168:171], v[198:201], v[92:95]
	v_mfma_f32_16x16x32_bf16 v[88:91], v[176:179], v[198:201], v[88:91]
	v_mfma_f32_16x16x32_bf16 v[76:79], v[168:171], v[206:209], v[76:79]
	v_mfma_f32_16x16x32_bf16 v[72:75], v[176:179], v[206:209], v[72:75]
	v_mfma_f32_16x16x32_bf16 v[68:71], v[168:171], v[214:217], v[68:71]
	v_mfma_f32_16x16x32_bf16 v[64:67], v[176:179], v[214:217], v[64:67]
	v_mfma_f32_16x16x32_bf16 v[108:111], v[172:175], v[194:197], v[108:111]
	v_mfma_f32_16x16x32_bf16 v[104:107], v[180:183], v[194:197], v[104:107]
	v_mfma_f32_16x16x32_bf16 v[92:95], v[172:175], v[202:205], v[92:95]
	v_mfma_f32_16x16x32_bf16 v[88:91], v[180:183], v[202:205], v[88:91]
	v_mfma_f32_16x16x32_bf16 v[76:79], v[172:175], v[210:213], v[76:79]
	v_mfma_f32_16x16x32_bf16 v[72:75], v[180:183], v[210:213], v[72:75]
	v_mfma_f32_16x16x32_bf16 v[68:71], v[172:175], v[218:221], v[68:71]
	v_mfma_f32_16x16x32_bf16 v[64:67], v[180:183], v[218:221], v[64:67]
	s_setprio 0
	s_barrier
	s_sub_u32 s92, s92, s21
	s_subb_u32 s93, s93, 0
	s_add_i32 m0, s15, 0x17f80
	ds_read_b128 v[190:193], v188 offset:49152
	ds_read_b128 v[194:197], v188 offset:50176
	ds_read_b128 v[198:201], v188 offset:51200
	ds_read_b128 v[202:205], v188 offset:52224
	ds_read_b128 v[206:209], v188 offset:53248
	ds_read_b128 v[210:213], v188 offset:54272
	ds_read_b128 v[214:217], v188 offset:55296
	ds_read_b128 v[218:221], v188 offset:56320
	global_load_lds_dwordx4 v148, s[92:93] offset:128
	s_add_i32 m0, s15, 0x19f80
	s_nop 0
	global_load_lds_dwordx4 v152, s[92:93] offset:128
	s_add_u32 s92, s92, s21
	s_addc_u32 s93, s93, 0
	s_add_i32 m0, s15, 0x1bf80
	s_add_u32 s6, s6, 0x100
	s_addc_u32 s7, s7, 0
	global_load_lds_dwordx4 v148, s[92:93] offset:128
	s_add_i32 m0, s15, 0x1df80
	s_sub_u32 s42, s42, s48
	s_subb_u32 s43, s43, 0
	global_load_lds_dwordx4 v152, s[92:93] offset:128
	s_add_i32 m0, s64, 0xffffff80
	s_add_u32 s8, s8, 0x100
	s_addc_u32 s66, s66, 0
	global_load_lds_dwordx4 v146, s[42:43] offset:128
	s_add_i32 m0, s65, 0xffffff80
	s_nop 0
	global_load_lds_dwordx4 v150, s[42:43] offset:128
	s_waitcnt vmcnt(8)
	s_waitcnt lgkmcnt(0)
	s_barrier
	s_setprio 1
	s_waitcnt lgkmcnt(0)
	v_mfma_f32_16x16x32_bf16 v[60:63], v[128:131], v[190:193], v[60:63]
	v_mfma_f32_16x16x32_bf16 v[56:59], v[136:139], v[190:193], v[56:59]
	v_mfma_f32_16x16x32_bf16 v[52:55], v[128:131], v[198:201], v[52:55]
	v_mfma_f32_16x16x32_bf16 v[48:51], v[136:139], v[198:201], v[48:51]
	v_mfma_f32_16x16x32_bf16 v[36:39], v[128:131], v[206:209], v[36:39]
	v_mfma_f32_16x16x32_bf16 v[32:35], v[136:139], v[206:209], v[32:35]
	v_mfma_f32_16x16x32_bf16 v[20:23], v[128:131], v[214:217], v[20:23]
	v_mfma_f32_16x16x32_bf16 v[16:19], v[136:139], v[214:217], v[16:19]
	v_mfma_f32_16x16x32_bf16 v[60:63], v[132:135], v[194:197], v[60:63]
	v_mfma_f32_16x16x32_bf16 v[56:59], v[140:143], v[194:197], v[56:59]
	v_mfma_f32_16x16x32_bf16 v[52:55], v[132:135], v[202:205], v[52:55]
	v_mfma_f32_16x16x32_bf16 v[48:51], v[140:143], v[202:205], v[48:51]
	v_mfma_f32_16x16x32_bf16 v[36:39], v[132:135], v[210:213], v[36:39]
	v_mfma_f32_16x16x32_bf16 v[32:35], v[140:143], v[210:213], v[32:35]
	v_mfma_f32_16x16x32_bf16 v[20:23], v[132:135], v[218:221], v[20:23]
	v_mfma_f32_16x16x32_bf16 v[16:19], v[140:143], v[218:221], v[16:19]
	s_setprio 0
	s_setprio 1
	v_mfma_f32_16x16x32_bf16 v[44:47], v[168:171], v[190:193], v[44:47]
	v_mfma_f32_16x16x32_bf16 v[40:43], v[176:179], v[190:193], v[40:43]
	v_mfma_f32_16x16x32_bf16 v[28:31], v[168:171], v[198:201], v[28:31]
	v_mfma_f32_16x16x32_bf16 v[24:27], v[176:179], v[198:201], v[24:27]
	v_mfma_f32_16x16x32_bf16 v[12:15], v[168:171], v[206:209], v[12:15]
	v_mfma_f32_16x16x32_bf16 v[8:11], v[176:179], v[206:209], v[8:11]
	v_mfma_f32_16x16x32_bf16 v[4:7], v[168:171], v[214:217], v[4:7]
	v_mfma_f32_16x16x32_bf16 v[0:3], v[176:179], v[214:217], v[0:3]
	v_mfma_f32_16x16x32_bf16 v[44:47], v[172:175], v[194:197], v[44:47]
	v_mfma_f32_16x16x32_bf16 v[40:43], v[180:183], v[194:197], v[40:43]
	v_mfma_f32_16x16x32_bf16 v[28:31], v[172:175], v[202:205], v[28:31]
	v_mfma_f32_16x16x32_bf16 v[24:27], v[180:183], v[202:205], v[24:27]
	v_mfma_f32_16x16x32_bf16 v[12:15], v[172:175], v[210:213], v[12:15]
	v_mfma_f32_16x16x32_bf16 v[8:11], v[180:183], v[210:213], v[8:11]
	v_mfma_f32_16x16x32_bf16 v[4:7], v[172:175], v[218:221], v[4:7]
	v_mfma_f32_16x16x32_bf16 v[0:3], v[180:183], v[218:221], v[0:3]
	s_setprio 0
	s_barrier
	s_cmp_ge_u32 s90, s55
	s_mov_b32 s42, s90
	s_cbranch_scc0 .LBB0_246
	s_and_b64 vcc, exec, s[86:87]
	s_cbranch_vccz .LBB0_249
	s_barrier
